# grid barrier: non-leader workgroups poll the top-level generation word directly (one round trip less per barrier)
# speedup vs baseline: 1.0006x; 1.0006x over previous
; __device__ __forceinline__ unsigned xb_ld(unsigned* p)              { return __hip_atomic_load(p, __ATOMIC_RELAXED, __HIP_MEMORY_SCOPE_AGENT); }
; __device__ __forceinline__ unsigned xb_add(unsigned* p, unsigned v) { return __hip_atomic_fetch_add(p, v, __ATOMIC_RELAXED, __HIP_MEMORY_SCOPE_AGENT); }
; #define XB_SPIN(cond, bar) do { unsigned _sp = 0; while (cond) { __builtin_amdgcn_s_sleep(1); \
;     if ((++_sp & 255u) == 0u) { if (xb_ld(&(bar)[XB_TMO])) break; if (_sp > XB_SPIN_CAP) { atomicAdd(&(bar)[XB_TMO], 1u); break; } } } } while (0)
; __device__ __forceinline__ void xcd_barrier(const XcdBarrier& b) {
;     ...
;         const unsigned old = xb_add(&bar[XB_XSUB(b.x)], 1u);
;         const unsigned gen = old / nloc;
;         if (old + 1u == (gen + 1u) * nloc) {
;             __builtin_amdgcn_fence(__ATOMIC_RELEASE, "agent");
;             asm volatile("s_waitcnt vmcnt(0)" ::: "memory");
;             const unsigned og = xb_add(&bar[XB_TOP], 1u);
;             const unsigned tg = og / nx;
;             if (og + 1u == (tg + 1u) * nx) xb_add(&bar[XB_TOPGEN], 1u);
;             else XB_SPIN(xb_ld(&bar[XB_TOPGEN]) == tg, bar);
;             __builtin_amdgcn_fence(__ATOMIC_ACQUIRE, "agent");
;             xb_add(&bar[XB_XGEN(b.x)], 1u);
;             asm volatile("s_waitcnt vmcnt(0)" ::: "memory");
;         } else {
;             XB_SPIN(xb_ld(&bar[XB_XGEN(b.x)]) == gen, bar);
.LBB0_406:
	global_atomic_add v8, v[168:169], v189, off sc0
	v_cvt_f32_u32_e32 v0, v3
	v_sub_u32_e32 v9, 0, v3
	v_rcp_iflag_f32_e32 v0, v0
	s_nop 0
	v_mul_f32_e32 v0, 0x4f7ffffe, v0
	v_cvt_u32_f32_e32 v0, v0
	v_mul_lo_u32 v9, v9, v0
	v_mul_hi_u32 v9, v0, v9
	v_add_u32_e32 v0, v0, v9
	s_waitcnt vmcnt(0)
	v_mul_hi_u32 v0, v8, v0
	v_mul_lo_u32 v9, v0, v3
	v_sub_u32_e32 v9, v8, v9
	v_add_u32_e32 v10, 1, v0
	v_cmp_ge_u32_e32 vcc, v9, v3
	v_add_u32_e32 v8, 1, v8
	s_nop 0
	v_cndmask_b32_e32 v0, v0, v10, vcc
	v_sub_u32_e32 v10, v9, v3
	v_cndmask_b32_e32 v9, v9, v10, vcc
	v_add_u32_e32 v10, 1, v0
	v_cmp_ge_u32_e32 vcc, v9, v3
	s_nop 1
	v_cndmask_b32_e32 v0, v0, v10, vcc
	v_mul_lo_u32 v9, v3, v0
	v_add_u32_e32 v3, v9, v3
	v_cmp_ne_u32_e32 vcc, v8, v3
	s_and_saveexec_b64 s[6:7], vcc
	s_xor_b64 s[6:7], exec, s[6:7]
	s_cbranch_execz .LBB0_420
	s_waitcnt lgkmcnt(0)
	v_readlane_b32 s4, v232, 21
	v_readlane_b32 s5, v232, 22
	s_nop 4
	global_load_dword v2, v1, s[4:5] sc1
	s_waitcnt vmcnt(0)
	v_cmp_eq_u32_e32 vcc, v2, v0
	s_and_saveexec_b64 s[8:9], vcc
	s_cbranch_execz .LBB0_419
	s_mov_b32 s20, 1
	s_mov_b64 s[10:11], 0
	s_branch .LBB0_410

; __device__ __forceinline__ unsigned xb_ld(unsigned* p)              { return __hip_atomic_load(p, __ATOMIC_RELAXED, __HIP_MEMORY_SCOPE_AGENT); }
; #define XB_SPIN(cond, bar) do { unsigned _sp = 0; while (cond) { __builtin_amdgcn_s_sleep(1); \
;     if ((++_sp & 255u) == 0u) { if (xb_ld(&(bar)[XB_TMO])) break; if (_sp > XB_SPIN_CAP) { atomicAdd(&(bar)[XB_TMO], 1u); break; } } } } while (0)
; __device__ __forceinline__ void xcd_barrier(const XcdBarrier& b) {
;     ...
;             XB_SPIN(xb_ld(&bar[XB_XGEN(b.x)]) == gen, bar);
.LBB0_414:
	v_readlane_b32 s4, v232, 21
	v_readlane_b32 s5, v232, 22
	s_nop 4
	global_load_dword v2, v1, s[4:5] sc1
	s_add_i32 s20, s20, 1
	s_mov_b64 s[16:17], -1
	s_waitcnt vmcnt(0)
	v_cmp_ne_u32_e32 vcc, v2, v0
	s_orn2_b64 s[14:15], vcc, exec
	s_branch .LBB0_409

; __device__ __forceinline__ unsigned xb_ld(unsigned* p)              { return __hip_atomic_load(p, __ATOMIC_RELAXED, __HIP_MEMORY_SCOPE_AGENT); }
; __device__ __forceinline__ unsigned xb_add(unsigned* p, unsigned v) { return __hip_atomic_fetch_add(p, v, __ATOMIC_RELAXED, __HIP_MEMORY_SCOPE_AGENT); }
; #define XB_SPIN(cond, bar) do { unsigned _sp = 0; while (cond) { __builtin_amdgcn_s_sleep(1); \
;     if ((++_sp & 255u) == 0u) { if (xb_ld(&(bar)[XB_TMO])) break; if (_sp > XB_SPIN_CAP) { atomicAdd(&(bar)[XB_TMO], 1u); break; } } } } while (0)
; __device__ __forceinline__ void xcd_barrier(const XcdBarrier& b) {
;     ...
;         const unsigned old = xb_add(&bar[XB_XSUB(b.x)], 1u);
;         const unsigned gen = old / nloc;
;         if (old + 1u == (gen + 1u) * nloc) {
;             __builtin_amdgcn_fence(__ATOMIC_RELEASE, "agent");
;             asm volatile("s_waitcnt vmcnt(0)" ::: "memory");
;             const unsigned og = xb_add(&bar[XB_TOP], 1u);
;             const unsigned tg = og / nx;
;             if (og + 1u == (tg + 1u) * nx) xb_add(&bar[XB_TOPGEN], 1u);
;             else XB_SPIN(xb_ld(&bar[XB_TOPGEN]) == tg, bar);
;             __builtin_amdgcn_fence(__ATOMIC_ACQUIRE, "agent");
;             xb_add(&bar[XB_XGEN(b.x)], 1u);
;             asm volatile("s_waitcnt vmcnt(0)" ::: "memory");
;         } else {
;             XB_SPIN(xb_ld(&bar[XB_XGEN(b.x)]) == gen, bar);
.LBB0_599:
	global_atomic_add v8, v[168:169], v189, off sc0
	v_cvt_f32_u32_e32 v0, v3
	v_sub_u32_e32 v9, 0, v3
	v_rcp_iflag_f32_e32 v0, v0
	s_nop 0
	v_mul_f32_e32 v0, 0x4f7ffffe, v0
	v_cvt_u32_f32_e32 v0, v0
	v_mul_lo_u32 v9, v9, v0
	v_mul_hi_u32 v9, v0, v9
	v_add_u32_e32 v0, v0, v9
	s_waitcnt vmcnt(0)
	v_mul_hi_u32 v0, v8, v0
	v_mul_lo_u32 v9, v0, v3
	v_sub_u32_e32 v9, v8, v9
	v_add_u32_e32 v10, 1, v0
	v_cmp_ge_u32_e32 vcc, v9, v3
	v_add_u32_e32 v8, 1, v8
	s_nop 0
	v_cndmask_b32_e32 v0, v0, v10, vcc
	v_sub_u32_e32 v10, v9, v3
	v_cndmask_b32_e32 v9, v9, v10, vcc
	v_add_u32_e32 v10, 1, v0
	v_cmp_ge_u32_e32 vcc, v9, v3
	s_nop 1
	v_cndmask_b32_e32 v0, v0, v10, vcc
	v_mul_lo_u32 v9, v3, v0
	v_add_u32_e32 v3, v9, v3
	v_cmp_ne_u32_e32 vcc, v8, v3
	s_and_saveexec_b64 s[4:5], vcc
	s_xor_b64 s[6:7], exec, s[4:5]
	s_cbranch_execz .LBB0_613
	s_waitcnt lgkmcnt(0)
	v_readlane_b32 s4, v232, 21
	v_readlane_b32 s5, v232, 22
	s_nop 4
	global_load_dword v2, v1, s[4:5] sc1
	s_waitcnt vmcnt(0)
	v_cmp_eq_u32_e32 vcc, v2, v0
	s_and_saveexec_b64 s[8:9], vcc
	s_cbranch_execz .LBB0_612
	s_mov_b32 s20, 1
	s_mov_b64 s[10:11], 0
	s_branch .LBB0_603
